# v6 + P2 V-load wait moved to consumer + band softmax row-max as v_max3 tree
# baseline (speedup 1.0000x reference)
.LBB0_286:
	s_ashr_i32 s44, s42, 8
	s_ashr_i32 s45, s44, 31
	s_lshl_b32 s34, s42, 6
	s_lshl_b64 s[44:45], s[44:45], 12
	s_and_b32 s65, s34, 0xfc0
	s_or_b32 s48, s44, s65
	s_mov_b32 s49, s45
	s_bfe_u32 s43, s42, 0x20006
	v_lshl_add_u64 v[0:1], s[48:49], 0, v[70:71]
	v_mov_b64_e32 v[8:9], s[60:61]
	s_mul_i32 s72, s43, 0xc0
	v_mad_u64_u32 v[2:3], s[46:47], v0, s54, v[8:9]
	v_mad_i32_i24 v3, v1, s54, v3
	s_lshl_b32 s34, s72, 1
	v_lshl_add_u64 v[0:1], v[2:3], 0, s[34:35]
	v_lshl_add_u64 v[2:3], s[48:49], 0, v[74:75]
	v_lshl_add_u64 v[10:11], s[48:49], 0, v[78:79]
	v_mad_u64_u32 v[4:5], s[46:47], v2, s54, v[8:9]
	v_mad_u64_u32 v[8:9], s[46:47], v10, s54, v[8:9]
	v_mad_i32_i24 v5, v3, s54, v5
	v_mad_i32_i24 v9, v11, s54, v9
	v_lshl_add_u64 v[2:3], v[4:5], 0, s[34:35]
	v_lshl_add_u64 v[8:9], v[8:9], 0, s[34:35]
	v_lshl_add_u64 v[0:1], v[72:73], 1, v[0:1]
	v_lshl_add_u64 v[4:5], v[76:77], 1, v[2:3]
	v_lshl_add_u64 v[8:9], v[80:81], 1, v[8:9]
	global_load_dwordx4 v[0:3], v[0:1], off offset:3072
	s_nop 0
	global_load_dwordx4 v[4:7], v[4:5], off offset:3072
	v_readfirstlane_b32 s64, v68
	global_load_dwordx4 v[8:11], v[8:9], off offset:3072
	s_waitcnt lgkmcnt(0)
	s_barrier
	s_and_saveexec_b64 s[46:47], s[0:1]
	s_cbranch_execz .LBB0_289
	v_lshl_add_u64 v[12:13], s[48:49], 0, v[68:69]
	v_lshlrev_b64 v[12:13], 5, v[12:13]
	v_lshl_add_u64 v[12:13], s[78:79], 0, v[12:13]
	s_lshl_b32 s34, s43, 2
	v_lshl_add_u64 v[14:15], v[12:13], 0, s[34:35]
	v_mov_b32_e32 v12, s34
	global_load_dword v16, v[14:15], off offset:16
	global_load_dword v17, v12, s[66:67] offset:16
	s_nop 0
	global_load_dword v12, v12, s[66:67]
	s_nop 0
	global_load_dword v13, v[14:15], off
	s_mov_b32 s43, 0xbfb8aa3b
	v_and_b32_e32 v14, 64, v108
	v_add_u32_e32 v15, -1, v108
	s_mov_b32 s34, 0x3f2aaaab
	v_cmp_lt_i32_e32 vcc, v15, v14
	s_waitcnt vmcnt(2)
	v_add_f32_e32 v16, v16, v17
	v_mul_f32_e64 v17, |v16|, s43
	v_exp_f32_e32 v18, v17
	v_min_f32_e32 v19, 0, v16
	v_cndmask_b32_e32 v15, v15, v108, vcc
	v_lshlrev_b32_e32 v15, 2, v15
	v_add_f32_e32 v20, 1.0, v18
	v_add_f32_e32 v21, -1.0, v20
	v_frexp_mant_f32_e32 v22, v20
	v_cvt_f64_f32_e32 v[16:17], v20
	v_sub_f32_e32 v23, v21, v20
	v_frexp_exp_i32_f64_e32 v16, v[16:17]
	v_cmp_gt_f32_e32 vcc, s34, v22
	v_sub_f32_e32 v21, v18, v21
	v_add_f32_e32 v17, 1.0, v23
	v_subbrev_co_u32_e32 v16, vcc, 0, v16, vcc
	v_add_f32_e32 v17, v21, v17
	v_sub_u32_e32 v21, 0, v16
	v_cvt_f32_i32_e32 v16, v16
	v_ldexp_f32 v20, v20, v21
	v_ldexp_f32 v17, v17, v21
	v_add_f32_e32 v21, -1.0, v20
	v_add_f32_e32 v22, 1.0, v20
	v_add_f32_e32 v23, 1.0, v21
	v_add_f32_e32 v24, -1.0, v22
	v_sub_f32_e32 v23, v20, v23
	v_sub_f32_e32 v20, v20, v24
	v_mul_f32_e32 v24, 0x3f317218, v16
	v_add_f32_e32 v23, v17, v23
	v_add_f32_e32 v17, v17, v20
	v_fma_f32 v20, v16, s55, -v24
	v_add_f32_e32 v25, v21, v23
	v_add_f32_e32 v26, v22, v17
	v_fmac_f32_e32 v20, 0xb102e308, v16
	v_sub_f32_e32 v16, v25, v21
	v_sub_f32_e32 v21, v26, v22
	v_rcp_f32_e32 v22, v26
	v_add_f32_e32 v27, v24, v20
	v_sub_f32_e32 v17, v17, v21
	v_sub_f32_e32 v21, v27, v24
	v_sub_f32_e32 v20, v20, v21
	v_mul_f32_e32 v21, v25, v22
	v_sub_f32_e32 v16, v23, v16
	v_mul_f32_e32 v23, v26, v21
	v_fma_f32 v24, v21, v26, -v23
	v_fmac_f32_e32 v24, v21, v17
	v_add_f32_e32 v28, v23, v24
	v_sub_f32_e32 v29, v25, v28
	v_sub_f32_e32 v23, v28, v23
	v_sub_f32_e32 v25, v25, v29
	v_sub_f32_e32 v23, v23, v24
	v_sub_f32_e32 v24, v25, v28
	v_add_f32_e32 v16, v16, v24
	v_add_f32_e32 v16, v23, v16
	v_add_f32_e32 v23, v29, v16
	v_mul_f32_e32 v24, v22, v23
	v_sub_f32_e32 v25, v29, v23
	v_mul_f32_e32 v28, v26, v24
	v_add_f32_e32 v16, v16, v25
	v_add_f32_e32 v25, v21, v24
	v_fma_f32 v26, v24, v26, -v28
	v_sub_f32_e32 v21, v25, v21
	v_fmac_f32_e32 v26, v24, v17
	v_sub_f32_e32 v17, v24, v21
	v_add_f32_e32 v21, v28, v26
	v_sub_f32_e32 v24, v21, v28
	v_sub_f32_e32 v28, v23, v21
	v_sub_f32_e32 v23, v23, v28
	v_sub_f32_e32 v21, v23, v21
	v_sub_f32_e32 v24, v24, v26
	v_add_f32_e32 v16, v16, v21
	v_add_f32_e32 v16, v24, v16
	v_add_f32_e32 v16, v28, v16
	v_mul_f32_e32 v16, v22, v16
	v_add_f32_e32 v16, v17, v16
	v_add_f32_e32 v17, v25, v16
	v_mul_f32_e32 v21, v17, v17
	v_fmamk_f32 v24, v21, 0x3e9b6dac, v100
	v_sub_f32_e32 v22, v17, v25
	v_ldexp_f32 v23, v17, 1
	v_mul_f32_e32 v17, v17, v21
	v_fmaak_f32 v21, v21, v24, 0x3f2aaada
	v_mul_f32_e32 v17, v17, v21
	v_add_f32_e32 v21, v23, v17
	v_sub_f32_e32 v16, v16, v22
	v_sub_f32_e32 v22, v21, v23
	v_ldexp_f32 v16, v16, 1
	v_sub_f32_e32 v17, v17, v22
	v_add_f32_e32 v16, v16, v17
	v_add_f32_e32 v17, v21, v16
	v_sub_f32_e32 v21, v17, v21
	v_add_f32_e32 v22, v27, v17
	v_sub_f32_e32 v16, v16, v21
	v_sub_f32_e32 v21, v22, v27
	v_sub_f32_e32 v23, v22, v21
	v_sub_f32_e32 v17, v17, v21
	v_add_f32_e32 v21, v20, v16
	v_sub_f32_e32 v23, v27, v23
	v_sub_f32_e32 v24, v21, v20
	v_add_f32_e32 v17, v17, v23
	v_sub_f32_e32 v23, v21, v24
	v_sub_f32_e32 v16, v16, v24
	v_sub_f32_e32 v20, v20, v23
	v_add_f32_e32 v17, v21, v17
	v_add_f32_e32 v16, v16, v20
	v_add_f32_e32 v20, v22, v17
	v_sub_f32_e32 v21, v20, v22
	v_sub_f32_e32 v17, v17, v21
	v_add_f32_e32 v16, v16, v17
	v_add_f32_e32 v16, v20, v16
	v_cmp_neq_f32_e32 vcc, s62, v18
	v_add_u32_e32 v17, -2, v108
	s_waitcnt vmcnt(0)
	v_add_f32_e32 v12, v13, v12
	v_cndmask_b32_e32 v16, v105, v16, vcc
	v_cmp_ngt_f32_e32 vcc, -1.0, v18
	s_nop 1
	v_cndmask_b32_e32 v16, v106, v16, vcc
	v_cmp_neq_f32_e32 vcc, -1.0, v18
	s_nop 1
	v_cndmask_b32_e32 v16, v107, v16, vcc
	v_cmp_lt_f32_e64 vcc, |v18|, s63
	s_nop 1
	v_cndmask_b32_e32 v16, v16, v18, vcc
	v_sub_f32_e32 v16, v19, v16
	ds_bpermute_b32 v15, v15, v16
	v_cmp_lt_i32_e32 vcc, v17, v14
	v_add_u32_e32 v18, 64, v14
	s_waitcnt lgkmcnt(0)
	v_add_f32_e32 v15, v16, v15
	v_cndmask_b32_e32 v17, v17, v108, vcc
	v_lshlrev_b32_e32 v17, 2, v17
	v_cndmask_b32_e64 v15, v15, v16, s[20:21]
	ds_bpermute_b32 v16, v17, v15
	v_add_u32_e32 v17, -4, v108
	v_cmp_lt_i32_e32 vcc, v17, v14
	s_waitcnt lgkmcnt(0)
	v_add_f32_e32 v16, v15, v16
	v_cndmask_b32_e32 v17, v17, v108, vcc
	v_lshlrev_b32_e32 v17, 2, v17
	v_cndmask_b32_e64 v15, v16, v15, s[4:5]
	ds_bpermute_b32 v16, v17, v15
	v_add_u32_e32 v17, -8, v108
	v_cmp_lt_i32_e32 vcc, v17, v14
	s_waitcnt lgkmcnt(0)
	v_add_f32_e32 v16, v15, v16
	v_cndmask_b32_e32 v17, v17, v108, vcc
	v_lshlrev_b32_e32 v17, 2, v17
	v_cndmask_b32_e64 v15, v16, v15, s[6:7]
	ds_bpermute_b32 v16, v17, v15
	v_add_u32_e32 v17, -16, v108
	v_cmp_lt_i32_e32 vcc, v17, v14
	s_waitcnt lgkmcnt(0)
	v_add_f32_e32 v16, v15, v16
	v_cndmask_b32_e32 v17, v17, v108, vcc
	v_lshlrev_b32_e32 v17, 2, v17
	v_cndmask_b32_e64 v15, v16, v15, s[8:9]
	ds_bpermute_b32 v16, v17, v15
	v_subrev_u32_e32 v17, 32, v108
	v_cmp_lt_i32_e32 vcc, v17, v14
	s_waitcnt lgkmcnt(0)
	v_add_f32_e32 v16, v15, v16
	v_cndmask_b32_e32 v17, v17, v108, vcc
	v_lshlrev_b32_e32 v17, 2, v17
	v_cndmask_b32_e64 v15, v16, v15, s[10:11]
	ds_bpermute_b32 v16, v17, v15
	v_xor_b32_e32 v17, 1, v108
	v_cmp_lt_i32_e32 vcc, v17, v18
	s_waitcnt lgkmcnt(0)
	v_add_f32_e32 v14, v15, v16
	v_cndmask_b32_e64 v15, v14, v15, s[12:13]
	ds_bpermute_b32 v14, v109, v15
	v_cndmask_b32_e32 v16, v108, v17, vcc
	v_lshlrev_b32_e32 v16, 2, v16
	s_waitcnt lgkmcnt(0)
	v_sub_f32_e32 v13, v14, v15
	v_add_f32_e32 v13, v12, v13
	ds_bpermute_b32 v12, v16, v13
	v_xor_b32_e32 v15, 2, v108
	v_cmp_lt_i32_e32 vcc, v15, v18
	v_xor_b32_e32 v16, 4, v108
	s_waitcnt lgkmcnt(0)
	v_max_f32_e32 v12, v12, v12
	v_cndmask_b32_e32 v15, v108, v15, vcc
	v_lshlrev_b32_e32 v15, 2, v15
	v_max_f32_e32 v12, v13, v12
	ds_bpermute_b32 v15, v15, v12
	v_cmp_lt_i32_e32 vcc, v16, v18
	s_waitcnt lgkmcnt(0)
	v_max_f32_e32 v15, v15, v15
	v_cndmask_b32_e32 v16, v108, v16, vcc
	v_lshlrev_b32_e32 v16, 2, v16
	v_max_f32_e32 v12, v12, v15
	ds_bpermute_b32 v15, v16, v12
	v_xor_b32_e32 v16, 8, v108
	v_cmp_lt_i32_e32 vcc, v16, v18
	s_waitcnt lgkmcnt(0)
	v_max_f32_e32 v15, v15, v15
	v_cndmask_b32_e32 v16, v108, v16, vcc
	v_lshlrev_b32_e32 v16, 2, v16
	v_max_f32_e32 v12, v12, v15
	ds_bpermute_b32 v15, v16, v12
	v_xor_b32_e32 v16, 16, v108
	v_cmp_lt_i32_e32 vcc, v16, v18
	s_waitcnt lgkmcnt(0)
	v_max_f32_e32 v15, v15, v15
	v_cndmask_b32_e32 v16, v108, v16, vcc
	v_lshlrev_b32_e32 v16, 2, v16
	v_max_f32_e32 v12, v12, v15
	ds_bpermute_b32 v15, v16, v12
	v_xor_b32_e32 v16, 32, v108
	v_cmp_lt_i32_e32 vcc, v16, v18
	s_waitcnt lgkmcnt(0)
	v_max_f32_e32 v15, v15, v15
	v_cndmask_b32_e32 v16, v108, v16, vcc
	v_max_f32_e32 v12, v12, v15
	v_lshlrev_b32_e32 v15, 2, v16
	ds_bpermute_b32 v15, v15, v12
	s_waitcnt lgkmcnt(0)
	v_max_f32_e32 v15, v15, v15
	v_max_f32_e32 v12, v12, v15
	v_sub_f32_e32 v13, v13, v12
	v_mul_f32_e32 v13, 0x3fb8aa3b, v13
	v_exp_f32_e32 v13, v13
	ds_write_b32 v91, v13 offset:51200
	s_and_b64 exec, exec, s[14:15]
	s_cbranch_execz .LBB0_289
	s_ashr_i32 s43, s42, 31
	s_lshl_b64 s[48:49], s[42:43], 2
	s_add_u32 s76, s50, s48
	s_addc_u32 s77, s51, s49
	s_add_u32 s48, s52, s48
	s_addc_u32 s49, s53, s49
	global_store_dword v85, v12, s[76:77]
	global_store_dword v85, v14, s[48:49]
.LBB0_289:
	s_or_b64 exec, exec, s[46:47]
	s_waitcnt vmcnt(0)
	ds_write_b128 v101, v[0:3] offset:25600
	ds_write_b128 v102, v[4:7] offset:25600
	ds_write_b128 v103, v[8:11] offset:25600
	s_waitcnt lgkmcnt(0)
	s_barrier
	s_and_saveexec_b64 s[46:47], s[16:17]
	s_cbranch_execz .LBB0_305
	v_add_u32_e32 v28, s72, v94
	v_add_u32_e32 v30, s65, v92
	v_ashrrev_i32_e32 v29, 31, v28
	v_lshl_add_u64 v[32:33], v[28:29], 1, s[60:61]
	v_cmp_lt_i32_e32 vcc, 2, v30
	v_mov_b32_e32 v4, 0
	v_mov_b32_e32 v0, 0
	v_mov_b32_e32 v1, 0
	v_mov_b32_e32 v2, 0
	v_mov_b32_e32 v3, 0
	s_and_saveexec_b64 s[48:49], vcc
	s_cbranch_execz .LBB0_292
	v_add_u32_e32 v84, -3, v30
	v_lshl_add_u64 v[0:1], s[44:45], 0, v[84:85]
	v_mad_u64_u32 v[2:3], s[72:73], v0, s54, v[32:33]
	v_mad_i32_i24 v3, v1, s54, v3
	global_load_dwordx4 v[0:3], v[2:3], off

.LBB0_1046:
	s_cmp_lt_i32 s30, s27
	s_cselect_b64 s[4:5], -1, 0
	s_cmp_gt_i32 s30, s3
	s_cselect_b64 s[6:7], -1, 0
	s_or_b64 s[4:5], s[4:5], s[6:7]
	s_and_b64 vcc, exec, s[4:5]
	s_cbranch_vccnz .LBB0_1056
	ds_read_b128 v[64:67], v125
	ds_read_b128 v[72:75], v125 offset:64
	s_add_i32 s4, s28, s30
	s_add_i32 s4, s4, 8
	s_cmp_lt_i32 s4, 6
	s_cselect_b64 s[4:5], -1, 0
	s_mov_b64 s[8:9], -1
	s_and_b64 vcc, exec, s[4:5]
	s_waitcnt lgkmcnt(1)
	v_mfma_f32_16x16x32_bf16 v[68:71], v[64:67], v[0:3], 0
	ds_read_b128 v[76:79], v125 offset:4672
	ds_read_b128 v[80:83], v125 offset:6976
	v_mfma_f32_16x16x32_bf16 v[64:67], v[64:67], v[8:11], 0
	s_waitcnt lgkmcnt(2)
	v_mfma_f32_16x16x32_bf16 v[84:87], v[72:75], v[12:15], v[64:67]
	v_mfma_f32_16x16x32_bf16 v[108:111], v[72:75], v[4:7], v[68:71]
	s_nop 4
	ds_read_b128 v[64:67], v125 offset:2304
	ds_read_b128 v[72:75], v125 offset:2368
	s_waitcnt lgkmcnt(1)
	v_mfma_f32_16x16x32_bf16 v[68:71], v[64:67], v[0:3], 0
	v_mfma_f32_16x16x32_bf16 v[64:67], v[64:67], v[8:11], 0
	s_waitcnt lgkmcnt(0)
	v_mfma_f32_16x16x32_bf16 v[104:107], v[72:75], v[4:7], v[68:71]
	v_mfma_f32_16x16x32_bf16 v[72:75], v[72:75], v[12:15], v[64:67]
	s_nop 4
	ds_read_b128 v[64:67], v125 offset:4608
	s_waitcnt lgkmcnt(0)
	v_mfma_f32_16x16x32_bf16 v[68:71], v[64:67], v[0:3], 0
	v_mfma_f32_16x16x32_bf16 v[64:67], v[64:67], v[8:11], 0
	v_mfma_f32_16x16x32_bf16 v[100:103], v[76:79], v[4:7], v[68:71]
	v_mfma_f32_16x16x32_bf16 v[68:71], v[76:79], v[12:15], v[64:67]
	s_nop 5
	ds_read_b128 v[64:67], v125 offset:6912
	s_waitcnt lgkmcnt(0)
	v_mfma_f32_16x16x32_bf16 v[76:79], v[64:67], v[0:3], 0
	v_mfma_f32_16x16x32_bf16 v[64:67], v[64:67], v[8:11], 0
	v_mfma_f32_16x16x32_bf16 v[96:99], v[80:83], v[4:7], v[76:79]
	v_mfma_f32_16x16x32_bf16 v[64:67], v[80:83], v[12:15], v[64:67]
	s_cbranch_vccz .LBB0_1072
	s_nop 3
	v_max3_f32 v77, v108, v109, v110
	v_max3_f32 v78, v104, v105, v106
	v_max3_f32 v77, v77, v111, v107
	v_max3_f32 v77, v77, v78, s95
	v_max3_f32 v78, v100, v101, v102
	v_max3_f32 v79, v96, v97, v98
	v_max3_f32 v78, v78, v103, v99
	v_max3_f32 v77, v77, v78, v79
	v_mov_b32_e32 v78, v77
	s_nop 1
	v_permlane16_swap_b32_e32 v77, v78
	ds_read_b32 v76, v153 offset:37628
	v_max_f32_e32 v77, v77, v78
	v_mov_b32_e32 v78, v77
	s_nop 1
	v_permlane32_swap_b32_e32 v77, v78
	v_max_f32_e32 v77, v77, v78
	s_waitcnt lgkmcnt(0)
	v_fmamk_f32 v77, v77, 0x3e38aa3b, v76
	v_sub_f32_e32 v78, v77, v139
	v_cmp_ge_f32_e32 vcc, s97, v78
	v_max_f32_e32 v78, v139, v139
	v_max_f32_e32 v77, v78, v77
	s_cmp_lg_u64 vcc, exec
	v_sub_f32_e32 v78, v139, v77
	s_cselect_b64 s[6:7], -1, 0
	v_exp_f32_e32 v78, v78
	v_cndmask_b32_e64 v145, v139, v77, s[6:7]
	v_sub_f32_e32 v95, v76, v145
	v_fmamk_f32 v76, v108, 0x3e38aa3b, v95
	v_exp_f32_e32 v76, v76
	v_fmamk_f32 v77, v109, 0x3e38aa3b, v95
	v_cndmask_b32_e64 v142, 1.0, v78, s[6:7]
	v_exp_f32_e32 v77, v77
	v_fmamk_f32 v78, v110, 0x3e38aa3b, v95
	v_exp_f32_e32 v78, v78
	v_fmamk_f32 v79, v111, 0x3e38aa3b, v95
	v_exp_f32_e32 v79, v79
	v_add_f32_e32 v80, 0, v76
	v_add_f32_e32 v80, v77, v80
	v_add_f32_e32 v80, v78, v80
	v_add_f32_e32 v88, v79, v80
	v_fmamk_f32 v80, v104, 0x3e38aa3b, v95
	v_exp_f32_e32 v80, v80
	v_fmamk_f32 v81, v105, 0x3e38aa3b, v95
	v_exp_f32_e32 v81, v81
	v_fmamk_f32 v82, v106, 0x3e38aa3b, v95
	v_exp_f32_e32 v82, v82
	v_fmamk_f32 v83, v107, 0x3e38aa3b, v95
	v_exp_f32_e32 v83, v83
	v_add_f32_e32 v88, v80, v88
	v_add_f32_e32 v88, v81, v88
	v_add_f32_e32 v88, v82, v88
	v_add_f32_e32 v92, v83, v88
	v_fmamk_f32 v88, v100, 0x3e38aa3b, v95
	v_exp_f32_e32 v88, v88
	v_fmamk_f32 v89, v101, 0x3e38aa3b, v95
	v_exp_f32_e32 v89, v89
	v_fmamk_f32 v90, v102, 0x3e38aa3b, v95
	v_exp_f32_e32 v90, v90
	v_fmamk_f32 v91, v103, 0x3e38aa3b, v95
	v_exp_f32_e32 v91, v91
	v_add_f32_e32 v92, v88, v92
	v_add_f32_e32 v92, v89, v92
	v_add_f32_e32 v92, v90, v92
	v_add_f32_e32 v146, v91, v92
	v_fmamk_f32 v92, v96, 0x3e38aa3b, v95
	v_exp_f32_e32 v92, v92
	v_fmamk_f32 v93, v97, 0x3e38aa3b, v95
	v_exp_f32_e32 v93, v93
	v_fmamk_f32 v94, v98, 0x3e38aa3b, v95
	v_exp_f32_e32 v94, v94
	v_fmac_f32_e32 v95, 0x3e38aa3b, v99
	v_exp_f32_e32 v95, v95
	v_add_f32_e32 v146, v92, v146
	v_add_f32_e32 v146, v93, v146
	v_add_f32_e32 v146, v94, v146
	v_add_f32_e32 v147, v95, v146
	s_cbranch_execz .LBB0_1073

.LBB0_1051:
	s_andn2_b64 vcc, exec, s[4:5]
	s_mov_b64 s[6:7], -1
	s_cbranch_vccnz .LBB0_1074
	v_max3_f32 v97, v84, v85, v86
	v_max3_f32 v98, v72, v73, v74
	v_max3_f32 v97, v97, v87, v75
	v_max3_f32 v97, v97, v98, s95
	v_max3_f32 v98, v68, v69, v70
	v_max3_f32 v99, v64, v65, v66
	v_max3_f32 v98, v98, v71, v67
	v_max3_f32 v97, v97, v98, v99
	v_mov_b32_e32 v98, v97
	s_nop 1
	v_permlane16_swap_b32_e32 v97, v98
	ds_read_b32 v96, v153 offset:37628
	v_max_f32_e32 v97, v97, v98
	v_mov_b32_e32 v98, v97
	s_nop 1
	v_permlane32_swap_b32_e32 v97, v98
	v_max_f32_e32 v97, v97, v98
	s_waitcnt lgkmcnt(0)
	v_fmamk_f32 v97, v97, 0x3e38aa3b, v96
	v_sub_f32_e32 v98, v97, v137
	v_cmp_ge_f32_e32 vcc, s97, v98
	v_max_f32_e32 v98, v137, v137
	v_max_f32_e32 v97, v98, v97
	s_cmp_lg_u64 vcc, exec
	v_sub_f32_e32 v98, v137, v97
	s_cselect_b64 s[4:5], -1, 0
	v_exp_f32_e32 v98, v98
	v_cndmask_b32_e64 v146, v137, v97, s[4:5]
	v_sub_f32_e32 v111, v96, v146
	v_fmamk_f32 v96, v84, 0x3e38aa3b, v111
	v_exp_f32_e32 v96, v96
	v_fmamk_f32 v97, v85, 0x3e38aa3b, v111
	v_cndmask_b32_e64 v142, 1.0, v98, s[4:5]
	v_exp_f32_e32 v97, v97
	v_fmamk_f32 v98, v86, 0x3e38aa3b, v111
	v_exp_f32_e32 v98, v98
	v_fmamk_f32 v99, v87, 0x3e38aa3b, v111
	v_exp_f32_e32 v99, v99
	v_add_f32_e32 v100, 0, v96
	v_add_f32_e32 v100, v97, v100
	v_add_f32_e32 v100, v98, v100
	v_add_f32_e32 v104, v99, v100
	v_fmamk_f32 v100, v72, 0x3e38aa3b, v111
	v_exp_f32_e32 v100, v100
	v_fmamk_f32 v101, v73, 0x3e38aa3b, v111
	v_exp_f32_e32 v101, v101
	v_fmamk_f32 v102, v74, 0x3e38aa3b, v111
	v_exp_f32_e32 v102, v102
	v_fmamk_f32 v103, v75, 0x3e38aa3b, v111
	v_exp_f32_e32 v103, v103
	v_add_f32_e32 v104, v100, v104
	v_add_f32_e32 v104, v101, v104
	v_add_f32_e32 v104, v102, v104
	v_add_f32_e32 v108, v103, v104
	v_fmamk_f32 v104, v68, 0x3e38aa3b, v111
	v_exp_f32_e32 v104, v104
	v_fmamk_f32 v105, v69, 0x3e38aa3b, v111
	v_exp_f32_e32 v105, v105
	v_fmamk_f32 v106, v70, 0x3e38aa3b, v111
	v_exp_f32_e32 v106, v106
	v_fmamk_f32 v107, v71, 0x3e38aa3b, v111
	v_exp_f32_e32 v107, v107
	v_add_f32_e32 v108, v104, v108
	v_add_f32_e32 v108, v105, v108
	v_add_f32_e32 v108, v106, v108
	v_add_f32_e32 v139, v107, v108
	v_fmamk_f32 v108, v64, 0x3e38aa3b, v111
	v_exp_f32_e32 v108, v108
	v_fmamk_f32 v109, v65, 0x3e38aa3b, v111
	v_exp_f32_e32 v109, v109
	v_fmamk_f32 v110, v66, 0x3e38aa3b, v111
	v_exp_f32_e32 v110, v110
	v_fmac_f32_e32 v111, 0x3e38aa3b, v67
	v_exp_f32_e32 v111, v111
	v_add_f32_e32 v139, v108, v139
	v_add_f32_e32 v139, v109, v139
	v_add_f32_e32 v139, v110, v139
	v_add_f32_e32 v139, v111, v139
	s_cbranch_execz .LBB0_1075

.LBB0_1059:
	s_cmp_lt_i32 s4, s27
	s_cselect_b64 s[4:5], -1, 0
	s_cmp_ge_i32 s30, s3
	s_cselect_b64 s[6:7], -1, 0
	s_or_b64 s[4:5], s[6:7], s[4:5]
	s_and_b64 vcc, exec, s[4:5]
	s_cbranch_vccnz .LBB0_1069
	ds_read_b128 v[64:67], v125 offset:9216
	ds_read_b128 v[72:75], v125 offset:9280
	s_add_i32 s4, s28, s30
	s_add_i32 s4, s4, 9
	s_cmp_lt_i32 s4, 6
	s_cselect_b64 s[4:5], -1, 0
	s_mov_b64 s[8:9], -1
	s_and_b64 vcc, exec, s[4:5]
	s_waitcnt lgkmcnt(1)
	v_mfma_f32_16x16x32_bf16 v[68:71], v[64:67], v[0:3], 0
	ds_read_b128 v[76:79], v125 offset:13888
	ds_read_b128 v[80:83], v125 offset:16192
	v_mfma_f32_16x16x32_bf16 v[64:67], v[64:67], v[8:11], 0
	s_waitcnt lgkmcnt(2)
	v_mfma_f32_16x16x32_bf16 v[84:87], v[72:75], v[12:15], v[64:67]
	v_mfma_f32_16x16x32_bf16 v[108:111], v[72:75], v[4:7], v[68:71]
	s_nop 4
	ds_read_b128 v[64:67], v125 offset:11520
	ds_read_b128 v[72:75], v125 offset:11584
	s_waitcnt lgkmcnt(1)
	v_mfma_f32_16x16x32_bf16 v[68:71], v[64:67], v[0:3], 0
	v_mfma_f32_16x16x32_bf16 v[64:67], v[64:67], v[8:11], 0
	s_waitcnt lgkmcnt(0)
	v_mfma_f32_16x16x32_bf16 v[104:107], v[72:75], v[4:7], v[68:71]
	v_mfma_f32_16x16x32_bf16 v[72:75], v[72:75], v[12:15], v[64:67]
	s_nop 4
	ds_read_b128 v[64:67], v125 offset:13824
	s_waitcnt lgkmcnt(0)
	v_mfma_f32_16x16x32_bf16 v[68:71], v[64:67], v[0:3], 0
	v_mfma_f32_16x16x32_bf16 v[64:67], v[64:67], v[8:11], 0
	v_mfma_f32_16x16x32_bf16 v[100:103], v[76:79], v[4:7], v[68:71]
	v_mfma_f32_16x16x32_bf16 v[68:71], v[76:79], v[12:15], v[64:67]
	s_nop 5
	ds_read_b128 v[64:67], v125 offset:16128
	s_waitcnt lgkmcnt(0)
	v_mfma_f32_16x16x32_bf16 v[76:79], v[64:67], v[0:3], 0
	v_mfma_f32_16x16x32_bf16 v[64:67], v[64:67], v[8:11], 0
	v_mfma_f32_16x16x32_bf16 v[96:99], v[80:83], v[4:7], v[76:79]
	v_mfma_f32_16x16x32_bf16 v[64:67], v[80:83], v[12:15], v[64:67]
	s_cbranch_vccz .LBB0_1076
	s_nop 3
	v_max3_f32 v77, v108, v109, v110
	v_max3_f32 v78, v104, v105, v106
	v_max3_f32 v77, v77, v111, v107
	v_max3_f32 v77, v77, v78, s95
	v_max3_f32 v78, v100, v101, v102
	v_max3_f32 v79, v96, v97, v98
	v_max3_f32 v78, v78, v103, v99
	v_max3_f32 v77, v77, v78, v79
	v_mov_b32_e32 v78, v77
	s_nop 1
	v_permlane16_swap_b32_e32 v77, v78
	ds_read_b32 v76, v153 offset:37628
	v_max_f32_e32 v77, v77, v78
	v_mov_b32_e32 v78, v77
	s_nop 1
	v_permlane32_swap_b32_e32 v77, v78
	v_max_f32_e32 v77, v77, v78
	s_waitcnt lgkmcnt(0)
	v_fmamk_f32 v77, v77, 0x3e38aa3b, v76
	v_sub_f32_e32 v78, v77, v145
	v_cmp_ge_f32_e32 vcc, s97, v78
	v_max_f32_e32 v78, v145, v145
	v_max_f32_e32 v77, v78, v77
	s_cmp_lg_u64 vcc, exec
	v_sub_f32_e32 v78, v145, v77
	s_cselect_b64 s[6:7], -1, 0
	v_exp_f32_e32 v78, v78
	v_cndmask_b32_e64 v139, v145, v77, s[6:7]
	v_sub_f32_e32 v95, v76, v139
	v_fmamk_f32 v76, v108, 0x3e38aa3b, v95
	v_exp_f32_e32 v76, v76
	v_fmamk_f32 v77, v109, 0x3e38aa3b, v95
	v_cndmask_b32_e64 v142, 1.0, v78, s[6:7]
	v_exp_f32_e32 v77, v77
	v_fmamk_f32 v78, v110, 0x3e38aa3b, v95
	v_exp_f32_e32 v78, v78
	v_fmamk_f32 v79, v111, 0x3e38aa3b, v95
	v_exp_f32_e32 v79, v79
	v_add_f32_e32 v80, 0, v76
	v_add_f32_e32 v80, v77, v80
	v_add_f32_e32 v80, v78, v80
	v_add_f32_e32 v88, v79, v80
	v_fmamk_f32 v80, v104, 0x3e38aa3b, v95
	v_exp_f32_e32 v80, v80
	v_fmamk_f32 v81, v105, 0x3e38aa3b, v95
	v_exp_f32_e32 v81, v81
	v_fmamk_f32 v82, v106, 0x3e38aa3b, v95
	v_exp_f32_e32 v82, v82
	v_fmamk_f32 v83, v107, 0x3e38aa3b, v95
	v_exp_f32_e32 v83, v83
	v_add_f32_e32 v88, v80, v88
	v_add_f32_e32 v88, v81, v88
	v_add_f32_e32 v88, v82, v88
	v_add_f32_e32 v92, v83, v88
	v_fmamk_f32 v88, v100, 0x3e38aa3b, v95
	v_exp_f32_e32 v88, v88
	v_fmamk_f32 v89, v101, 0x3e38aa3b, v95
	v_exp_f32_e32 v89, v89
	v_fmamk_f32 v90, v102, 0x3e38aa3b, v95
	v_exp_f32_e32 v90, v90
	v_fmamk_f32 v91, v103, 0x3e38aa3b, v95
	v_exp_f32_e32 v91, v91
	v_add_f32_e32 v92, v88, v92
	v_add_f32_e32 v92, v89, v92
	v_add_f32_e32 v92, v90, v92
	v_add_f32_e32 v137, v91, v92
	v_fmamk_f32 v92, v96, 0x3e38aa3b, v95
	v_exp_f32_e32 v92, v92
	v_fmamk_f32 v93, v97, 0x3e38aa3b, v95
	v_exp_f32_e32 v93, v93
	v_fmamk_f32 v94, v98, 0x3e38aa3b, v95
	v_exp_f32_e32 v94, v94
	v_fmac_f32_e32 v95, 0x3e38aa3b, v99
	v_exp_f32_e32 v95, v95
	v_add_f32_e32 v137, v92, v137
	v_add_f32_e32 v137, v93, v137
	v_add_f32_e32 v137, v94, v137
	v_add_f32_e32 v147, v95, v137
	s_cbranch_execz .LBB0_1077

.LBB0_1064:
	s_andn2_b64 vcc, exec, s[4:5]
	s_mov_b64 s[6:7], -1
	s_cbranch_vccnz .LBB0_1078
	v_max3_f32 v97, v84, v85, v86
	v_max3_f32 v98, v72, v73, v74
	v_max3_f32 v97, v97, v87, v75
	v_max3_f32 v97, v97, v98, s95
	v_max3_f32 v98, v68, v69, v70
	v_max3_f32 v99, v64, v65, v66
	v_max3_f32 v98, v98, v71, v67
	v_max3_f32 v97, v97, v98, v99
	v_mov_b32_e32 v98, v97
	s_nop 1
	v_permlane16_swap_b32_e32 v97, v98
	ds_read_b32 v96, v153 offset:37628
	v_max_f32_e32 v97, v97, v98
	v_mov_b32_e32 v98, v97
	s_nop 1
	v_permlane32_swap_b32_e32 v97, v98
	v_max_f32_e32 v97, v97, v98
	s_waitcnt lgkmcnt(0)
	v_fmamk_f32 v97, v97, 0x3e38aa3b, v96
	v_sub_f32_e32 v98, v97, v146
	v_cmp_ge_f32_e32 vcc, s97, v98
	v_max_f32_e32 v98, v146, v146
	v_max_f32_e32 v97, v98, v97
	s_cmp_lg_u64 vcc, exec
	v_sub_f32_e32 v98, v146, v97
	s_cselect_b64 s[4:5], -1, 0
	v_exp_f32_e32 v98, v98
	v_cndmask_b32_e64 v137, v146, v97, s[4:5]
	v_sub_f32_e32 v111, v96, v137
	v_fmamk_f32 v96, v84, 0x3e38aa3b, v111
	v_exp_f32_e32 v96, v96
	v_fmamk_f32 v97, v85, 0x3e38aa3b, v111
	v_cndmask_b32_e64 v142, 1.0, v98, s[4:5]
	v_exp_f32_e32 v97, v97
	v_fmamk_f32 v98, v86, 0x3e38aa3b, v111
	v_exp_f32_e32 v98, v98
	v_fmamk_f32 v99, v87, 0x3e38aa3b, v111
	v_exp_f32_e32 v99, v99
	v_add_f32_e32 v100, 0, v96
	v_add_f32_e32 v100, v97, v100
	v_add_f32_e32 v100, v98, v100
	v_add_f32_e32 v104, v99, v100
	v_fmamk_f32 v100, v72, 0x3e38aa3b, v111
	v_exp_f32_e32 v100, v100
	v_fmamk_f32 v101, v73, 0x3e38aa3b, v111
	v_exp_f32_e32 v101, v101
	v_fmamk_f32 v102, v74, 0x3e38aa3b, v111
	v_exp_f32_e32 v102, v102
	v_fmamk_f32 v103, v75, 0x3e38aa3b, v111
	v_exp_f32_e32 v103, v103
	v_add_f32_e32 v104, v100, v104
	v_add_f32_e32 v104, v101, v104
	v_add_f32_e32 v104, v102, v104
	v_add_f32_e32 v108, v103, v104
	v_fmamk_f32 v104, v68, 0x3e38aa3b, v111
	v_exp_f32_e32 v104, v104
	v_fmamk_f32 v105, v69, 0x3e38aa3b, v111
	v_exp_f32_e32 v105, v105
	v_fmamk_f32 v106, v70, 0x3e38aa3b, v111
	v_exp_f32_e32 v106, v106
	v_fmamk_f32 v107, v71, 0x3e38aa3b, v111
	v_exp_f32_e32 v107, v107
	v_add_f32_e32 v108, v104, v108
	v_add_f32_e32 v108, v105, v108
	v_add_f32_e32 v108, v106, v108
	v_add_f32_e32 v145, v107, v108
	v_fmamk_f32 v108, v64, 0x3e38aa3b, v111
	v_exp_f32_e32 v108, v108
	v_fmamk_f32 v109, v65, 0x3e38aa3b, v111
	v_exp_f32_e32 v109, v109
	v_fmamk_f32 v110, v66, 0x3e38aa3b, v111
	v_exp_f32_e32 v110, v110
	v_fmac_f32_e32 v111, 0x3e38aa3b, v67
	v_exp_f32_e32 v111, v111
	v_add_f32_e32 v145, v108, v145
	v_add_f32_e32 v145, v109, v145
	v_add_f32_e32 v145, v110, v145
	v_add_f32_e32 v145, v111, v145
	s_cbranch_execz .LBB0_1079
